# FFN-up bubbles: first 512 w1 tiles of each bubble weight conversion moved into P0 weight prep (dormant ffn2_w1 loop; ffn1_w1 loop at l=1), bubbles start at tile 512
# speedup vs baseline: 1.0029x; 1.0029x over previous
.LBB0_19:
	v_mov_b32_e32 v0, v194
	s_xor_b64 s[0:1], s[4:5], -1
	s_andn2_b64 vcc, exec, s[0:1]
	v_readfirstlane_b32 s2, v0
	s_ashr_i32 s13, s2, 8
	v_readlane_b32 s2, v254, 41
	v_cndmask_b32_e64 v0, 0, 1, s[0:1]
	s_add_i32 s12, s13, s2
	s_mul_i32 s13, s13, 0x12000
	v_cmp_ne_u32_e64 s[4:5], 1, v0
	s_movk_i32 s57, 0x580
	s_cbranch_vccz .Lffn1_full
	s_movk_i32 s57, 0x200
.Lffn1_full:
	v_mov_b32_e32 v0, v194
	s_cmp_ge_i32 s12, s57
	s_cbranch_scc1 .LBB0_27
	v_lshlrev_b32_e32 v2, 2, v0
	v_and_b32_e32 v20, 60, v2
	v_lshlrev_b32_e32 v2, 4, v0
	v_readlane_b32 s0, v254, 51
	v_and_b32_e32 v2, 48, v2
	s_mul_i32 s88, s0, 0x580000
	v_readlane_b32 s40, v251, 6
	v_mul_u32_u24_e32 v6, 0x41, v2
	s_lshl_b64 s[0:1], s[88:89], 2
	v_readlane_b32 s44, v251, 10
	v_bfe_u32 v3, v0, 4, 4
	v_bfe_u32 v21, v0, 2, 6
	v_lshlrev_b32_e32 v6, 2, v6
	v_and_b32_e32 v0, 0xfc, v0
	s_mul_i32 s2, s12, 0x58000
	v_readlane_b32 s45, v251, 11
	s_add_u32 s0, s44, s0
	v_lshl_add_u32 v4, v20, 2, s13
	v_mul_u32_u24_e32 v5, 0x104, v3
	v_add3_u32 v22, s13, v6, v0
	v_add3_u32 v23, s13, v0, v6
	v_mov_b32_e32 v0, s2
	s_addc_u32 s1, s45, s1
	v_mad_u32_u24 v24, v3, s70, v0
	s_lshl_b32 s2, s12, 6
	s_lshl_b32 s10, s82, 6
	v_add_u32_e32 v25, v4, v5
	v_lshlrev_b32_e32 v0, 1, v2
	s_mov_b32 s11, s12
	v_readlane_b32 s41, v251, 7
	v_readlane_b32 s42, v251, 8
	v_readlane_b32 s43, v251, 9
	v_readlane_b32 s46, v251, 12
	v_readlane_b32 s47, v251, 13
	v_readlane_b32 s48, v251, 14
	v_readlane_b32 s49, v251, 15
	v_readlane_b32 s50, v251, 16
	v_readlane_b32 s51, v251, 17
	v_readlane_b32 s52, v251, 18
	v_readlane_b32 s53, v251, 19
	v_readlane_b32 s54, v251, 20
	v_readlane_b32 s55, v251, 21
	s_branch .LBB0_23
.LBB0_22:
	s_or_b64 exec, exec, s[6:7]
	s_add_i32 s11, s11, s82
	s_add_i32 s2, s2, s10
	s_mul_i32 s6, s82, 0x58000
	s_cmp_lt_i32 s11, s57
	v_add_u32_e32 v24, s6, v24
	s_barrier
	s_cbranch_scc0 .LBB0_27

.LBB0_27:
	v_readlane_b32 s0, v252, 7
	v_readlane_b32 s1, v252, 8
	s_andn2_b64 vcc, exec, s[0:1]
	s_nop 0
	v_cndmask_b32_e64 v0, 0, 1, s[0:1]
	v_cmp_ne_u32_e64 s[6:7], 1, v0
	s_nop 0
	v_mov_b32_e32 v0, v194
	s_cmpk_gt_i32 s12, 0x1ff
	s_cbranch_scc1 .LBB0_35
	v_lshlrev_b32_e32 v2, 2, v0
	v_and_b32_e32 v20, 60, v2
	v_lshlrev_b32_e32 v2, 4, v0
	v_readlane_b32 s0, v254, 51
	v_and_b32_e32 v2, 48, v2
	s_mul_i32 s88, s0, 0x580000
	v_readlane_b32 s40, v251, 38
	v_mul_u32_u24_e32 v6, 0x41, v2
	s_lshl_b64 s[0:1], s[88:89], 2
	v_readlane_b32 s48, v251, 46
	v_bfe_u32 v3, v0, 4, 4
	v_bfe_u32 v21, v0, 2, 6
	v_lshlrev_b32_e32 v6, 2, v6
	v_and_b32_e32 v0, 0xfc, v0
	s_mul_i32 s2, s12, 0x58000
	v_readlane_b32 s49, v251, 47
	s_add_u32 s0, s48, s0
	v_lshl_add_u32 v4, v20, 2, s13
	v_mul_u32_u24_e32 v5, 0x104, v3
	v_add3_u32 v22, s13, v6, v0
	v_add3_u32 v23, s13, v0, v6
	v_mov_b32_e32 v0, s2
	s_addc_u32 s1, s49, s1
	v_mad_u32_u24 v24, v3, s70, v0
	s_lshl_b32 s2, s12, 6
	s_lshl_b32 s14, s82, 6
	v_add_u32_e32 v25, v4, v5
	v_lshlrev_b32_e32 v0, 1, v2
	s_mov_b32 s15, s12
	v_readlane_b32 s41, v251, 39
	v_readlane_b32 s42, v251, 40
	v_readlane_b32 s43, v251, 41
	v_readlane_b32 s44, v251, 42
	v_readlane_b32 s45, v251, 43
	v_readlane_b32 s46, v251, 44
	v_readlane_b32 s47, v251, 45
	v_readlane_b32 s50, v251, 48
	v_readlane_b32 s51, v251, 49
	v_readlane_b32 s52, v251, 50
	v_readlane_b32 s53, v251, 51
	v_readlane_b32 s54, v251, 52
	v_readlane_b32 s55, v251, 53
	s_branch .LBB0_31
.LBB0_30:
	s_or_b64 exec, exec, s[8:9]
	s_add_i32 s15, s15, s82
	s_add_i32 s2, s2, s14
	s_mul_i32 s8, s82, 0x58000
	s_cmpk_lt_i32 s15, 0x200
	v_add_u32_e32 v24, s8, v24
	s_barrier
	s_cbranch_scc0 .LBB0_35

.LBB0_199:
	v_readlane_b32 s0, v252, 44
	v_readlane_b32 s1, v252, 45
	s_andn2_b64 vcc, exec, s[0:1]
	s_cbranch_vccnz .LBB0_218
	v_mov_b32_e32 v0, v194
	s_nop 0
	v_readfirstlane_b32 s0, v0
	s_ashr_i32 s6, s0, 8
	v_readlane_b32 s0, v254, 41
	s_add_i32 s7, s6, s0
	s_add_i32 s2, s7, 0xffffff00
	s_add_i32 s56, s2, 0x200
	s_mul_i32 s6, s6, 0x12000
	v_mov_b32_e32 v0, v194
	s_cmpk_gt_i32 s7, 0x67f
	s_cbranch_scc1 .LBB0_209
	v_lshlrev_b32_e32 v2, 2, v0
	v_and_b32_e32 v12, 60, v2
	v_lshlrev_b32_e32 v2, 4, v0
	v_and_b32_e32 v2, 48, v2
	v_readlane_b32 s0, v254, 51
	v_readlane_b32 s40, v251, 38
	v_mul_u32_u24_e32 v6, 0x41, v2
	s_mul_i32 s0, s0, 0x1600000
	v_readlane_b32 s48, v251, 46
	v_bfe_u32 v3, v0, 4, 4
	v_bfe_u32 v13, v0, 2, 6
	v_lshlrev_b32_e32 v6, 2, v6
	v_and_b32_e32 v0, 0xfc, v0
	s_mul_i32 s4, s56, 0x58000
	v_readlane_b32 s49, v251, 47
	s_add_u32 s0, s48, s0
	v_lshl_add_u32 v4, v12, 2, s6
	v_mul_u32_u24_e32 v5, 0x104, v3
	v_add3_u32 v14, s6, v6, v0
	v_add3_u32 v15, s6, v0, v6
	v_mov_b32_e32 v0, s4
	s_addc_u32 s1, s49, 0
	v_mad_u32_u24 v16, v3, s70, v0
	s_lshl_b32 s8, s56, 6
	v_lshlrev_b32_e32 v0, 1, v2
	v_add_u32_e32 v17, v4, v5
	s_mov_b32 s9, s56
	v_readlane_b32 s41, v251, 39
	v_readlane_b32 s42, v251, 40
	v_readlane_b32 s43, v251, 41
	v_readlane_b32 s44, v251, 42
	v_readlane_b32 s45, v251, 43
	v_readlane_b32 s46, v251, 44
	v_readlane_b32 s47, v251, 45
	v_readlane_b32 s50, v251, 48
	v_readlane_b32 s51, v251, 49
	v_readlane_b32 s52, v251, 50
	v_readlane_b32 s53, v251, 51
	v_readlane_b32 s54, v251, 52
	v_readlane_b32 s55, v251, 53
	s_branch .LBB0_203

.LBB0_1488:
	v_readlane_b32 s0, v252, 40
	v_readlane_b32 s4, v254, 61
	v_readlane_b32 s1, v252, 41
	v_readlane_b32 s5, v254, 62
	s_and_b64 s[0:1], s[0:1], s[4:5]
	v_readlane_b32 s4, v252, 42
	v_readlane_b32 s5, v252, 43
	s_and_b64 s[4:5], s[4:5], s[0:1]
	s_andn2_b64 vcc, exec, s[4:5]
	s_cbranch_vccnz .LBB0_1507
	v_mov_b32_e32 v0, v194
	s_nop 0
	v_readfirstlane_b32 s2, v0
	s_ashr_i32 s6, s2, 8
	v_readlane_b32 s2, v254, 41
	s_add_i32 s7, s6, s2
	s_add_i32 s2, s7, 0xffffff00
	s_add_i32 s56, s2, 0x200
	s_mul_i32 s6, s6, 0x12000
	v_mov_b32_e32 v0, v194
	s_cmpk_gt_i32 s7, 0x67f
	s_cbranch_scc1 .LBB0_1498
	v_lshlrev_b32_e32 v2, 2, v0
	v_and_b32_e32 v12, 60, v2
	v_lshlrev_b32_e32 v2, 4, v0
	v_and_b32_e32 v2, 48, v2
	v_mul_u32_u24_e32 v6, 0x41, v2
	v_bfe_u32 v3, v0, 4, 4
	v_bfe_u32 v13, v0, 2, 6
	v_lshlrev_b32_e32 v6, 2, v6
	v_and_b32_e32 v0, 0xfc, v0
	s_mul_i32 s4, s56, 0x58000
	v_lshl_add_u32 v4, v12, 2, s6
	v_mul_u32_u24_e32 v5, 0x104, v3
	v_add3_u32 v14, s6, v6, v0
	v_add3_u32 v15, s6, v0, v6
	v_mov_b32_e32 v0, s4
	v_mad_u32_u24 v16, v3, s70, v0
	s_lshl_b32 s8, s56, 6
	v_lshlrev_b32_e32 v0, 1, v2
	v_add_u32_e32 v17, v4, v5
	s_mov_b32 s9, s56
	s_branch .LBB0_1492
